# v35 + nt on the N-phase loads of the f32 input rows (streamed, evicted long before their re-read)
# speedup vs baseline: 1.0036x; 1.0002x over previous
; #define GAS __attribute__((address_space(1)))
; __device__ __forceinline__ void ln_rows(const Frame& F, const float* src, float* dstf, bf16* dstb, float* must, const float* gam, const float* bet, int nrows, bool poison) {
;     const int gw = F.vcu * NWAVES + F.wave, NGW = F.G * NWAVES;
;     f32x4 vn[8];
;     if (gw < nrows) { const GAS f32x4* xr = (const GAS f32x4*)(src + (size_t)gw * DM) + F.lane;
; #pragma unroll
;         for (int j = 0; j < 8; ++j) vn[j] = xr[64 * j]; }
;     for (int m = gw; m < nrows; m += NGW) {
;         f32x4 v[8]; float s = 0.f;
; #pragma unroll
;         for (int j = 0; j < 8; ++j) { v[j] = vn[j]; s += (v[j].x + v[j].y) + (v[j].z + v[j].w); }
;         if (m + NGW < nrows) { const GAS f32x4* xr = (const GAS f32x4*)(src + (size_t)(m + NGW) * DM) + F.lane;
; #pragma unroll
;             for (int j = 0; j < 8; ++j) vn[j] = xr[64 * j]; }
.LBB0_201:
	s_lshl_b32 s8, s33, 3
	s_add_i32 s8, s8, s28
	s_lshl_b32 s10, s97, 3
	s_cmpk_lt_i32 s8, 0x4000
	s_mov_b32 s14, 21
	s_mov_b32 s16, 32
	s_mov_b32 s18, 3
	s_mov_b32 s20, 4
	s_cselect_b64 s[12:13], -1, 0
	s_cmpk_gt_i32 s8, 0x3fff
	s_cbranch_scc1 .LBB0_210
	s_ashr_i32 s15, s14, 31
	s_lshl_b64 s[14:15], s[14:15], 3
	s_add_u32 s14, s0, s14
	s_addc_u32 s15, s1, s15
	s_ashr_i32 s17, s16, 31
	s_lshl_b64 s[16:17], s[16:17], 3
	s_add_u32 s16, s0, s16
	s_addc_u32 s17, s1, s17
	s_ashr_i32 s19, s18, 31
	s_lshl_b64 s[18:19], s[18:19], 3
	s_add_u32 s18, s0, s18
	s_addc_u32 s19, s1, s19
	s_ashr_i32 s21, s20, 31
	s_lshl_b64 s[20:21], s[20:21], 3
	s_add_u32 s20, s0, s20
	s_addc_u32 s21, s1, s21
	s_ashr_i32 s9, s8, 31
	s_lshl_b64 s[22:23], s[8:9], 13
	s_add_u32 s22, s6, s22
	s_addc_u32 s23, s7, s23
	v_lshlrev_b64 v[14:15], 4, v[226:227]
	v_lshl_add_u64 v[16:17], s[22:23], 0, v[14:15]
	s_movk_i32 s11, 0x1000
	v_add_co_u32_e32 v18, vcc, s11, v16
	global_load_dwordx4 v[58:61], v[16:17], off offset:1024 nt
	global_load_dwordx4 v[54:57], v[16:17], off offset:2048 nt
	global_load_dwordx4 v[50:53], v[16:17], off offset:3072 nt
	v_addc_co_u32_e32 v19, vcc, 0, v17, vcc
	global_load_dwordx4 v[2:5], v[18:19], off offset:3072 nt
	global_load_dwordx4 v[6:9], v[18:19], off offset:2048 nt
	global_load_dwordx4 v[10:13], v[18:19], off offset:1024 nt
	global_load_dwordx4 v[30:33], v[18:19], off nt
	global_load_dwordx4 v[62:65], v[16:17], off nt
	s_load_dwordx2 s[18:19], s[18:19], 0x0
	s_nop 0
	s_load_dwordx2 s[22:23], s[14:15], 0x0
	s_nop 0
	s_load_dwordx2 s[14:15], s[20:21], 0x0
	s_nop 0
	s_load_dwordx2 s[20:21], s[16:17], 0x0
	v_lshlrev_b32_e32 v16, 2, v226
	v_lshlrev_b32_e32 v22, 4, v226
	v_cmp_eq_u32_e32 vcc, 0, v226
	v_mov_b32_e32 v17, v227
	s_waitcnt lgkmcnt(0)
	s_cmp_lg_u64 s[20:21], 0
	v_mov_b32_e32 v19, v227
	v_mov_b32_e32 v21, v227
	v_mov_b32_e32 v23, v227
	v_xor_b32_e32 v1, 4, v16
	v_xor_b32_e32 v92, 8, v16
	v_xor_b32_e32 v93, 16, v16
	v_xor_b32_e32 v94, 32, v16
	v_xor_b32_e32 v95, 64, v16
	v_xor_b32_e32 v96, 0x80, v16
	v_or_b32_e32 v16, 0x1000, v22
	v_or_b32_e32 v18, 0x1400, v22
	v_or_b32_e32 v20, 0x1800, v22
	v_or_b32_e32 v22, 0x1c00, v22
	s_cselect_b64 s[16:17], -1, 0
	s_cmp_lg_u64 s[22:23], 0
	v_lshl_add_u64 v[66:67], s[18:19], 0, v[14:15]
	v_lshl_add_u64 v[68:69], s[18:19], 0, v[16:17]
	v_lshl_add_u64 v[70:71], s[18:19], 0, v[18:19]
	v_lshl_add_u64 v[72:73], s[18:19], 0, v[20:21]
	v_lshl_add_u64 v[74:75], s[18:19], 0, v[22:23]
	v_lshl_add_u64 v[76:77], s[14:15], 0, v[14:15]
	v_lshl_add_u64 v[78:79], s[14:15], 0, v[16:17]
	v_lshl_add_u64 v[80:81], s[14:15], 0, v[18:19]
	v_lshl_add_u64 v[82:83], s[14:15], 0, v[20:21]
	v_lshl_add_u64 v[84:85], s[14:15], 0, v[22:23]
	s_cselect_b64 s[14:15], -1, 0
	s_and_b64 s[16:17], s[16:17], vcc
	s_lshl_b64 s[18:19], s[8:9], 3
	s_add_u32 s18, s20, s18
	s_addc_u32 s19, s21, s19
	s_ashr_i32 s11, s10, 31
	s_lshl_b64 s[24:25], s[8:9], 12
	s_lshl_b64 s[20:21], s[10:11], 3
	s_add_u32 s24, s22, s24
	s_addc_u32 s25, s23, s25
	s_add_i32 s26, s8, s10
	v_lshlrev_b32_e32 v24, 3, v226
	v_mov_b32_e32 v25, v227
	s_ashr_i32 s27, s26, 31
	s_lshl_b64 s[22:23], s[10:11], 12
	v_lshl_add_u64 v[86:87], s[24:25], 0, v[24:25]
	s_lshl_b64 s[24:25], s[26:27], 13
	s_add_u32 s6, s6, s24
	s_addc_u32 s7, s7, s25
	v_lshl_add_u64 v[14:15], s[6:7], 0, v[14:15]
	s_mov_b64 s[6:7], 0x1000
	v_lshl_add_u64 v[88:89], v[14:15], 0, s[6:7]
	s_mov_b32 s28, s8
	s_lshl_b64 s[24:25], s[10:11], 13
	s_waitcnt vmcnt(0)
	v_mov_b64_e32 v[22:23], v[58:59]
	v_mov_b64_e32 v[18:19], v[54:55]
	v_mov_b64_e32 v[14:15], v[50:51]
	v_mov_b64_e32 v[36:37], v[4:5]
	v_mov_b64_e32 v[40:41], v[8:9]
	v_mov_b64_e32 v[44:45], v[12:13]
	v_mov_b64_e32 v[48:49], v[32:33]
	v_mov_b64_e32 v[26:27], v[62:63]
	v_mov_b64_e32 v[16:17], v[52:53]
	v_mov_b64_e32 v[20:21], v[56:57]
	v_mov_b64_e32 v[24:25], v[60:61]
	v_mov_b64_e32 v[34:35], v[2:3]
	v_mov_b64_e32 v[38:39], v[6:7]
	v_mov_b64_e32 v[42:43], v[10:11]
	v_mov_b64_e32 v[46:47], v[30:31]
	v_mov_b64_e32 v[28:29], v[64:65]
	s_branch .LBB0_204

; #define GAS __attribute__((address_space(1)))
; __device__ __forceinline__ void ln_rows(const Frame& F, const float* src, float* dstf, bf16* dstb, float* must, const float* gam, const float* bet, int nrows, bool poison) {
;     ...
;     for (int m = gw; m < nrows; m += NGW) {
;         f32x4 v[8]; float s = 0.f;
; #pragma unroll
;         for (int j = 0; j < 8; ++j) { v[j] = vn[j]; s += (v[j].x + v[j].y) + (v[j].z + v[j].w); }
;         if (m + NGW < nrows) { const GAS f32x4* xr = (const GAS f32x4*)(src + (size_t)(m + NGW) * DM) + F.lane;
; #pragma unroll
;             for (int j = 0; j < 8; ++j) vn[j] = xr[64 * j]; }
.LBB0_204:
	s_add_i32 s28, s28, s10
	s_cmpk_gt_i32 s28, 0x3fff
	s_cselect_b64 s[26:27], -1, 0
	s_and_b64 vcc, exec, s[26:27]
	s_cbranch_vccnz .LBB0_206
	global_load_dwordx4 v[26:29], v[88:89], off offset:-4096 nt
	global_load_dwordx4 v[22:25], v[88:89], off offset:-3072 nt
	global_load_dwordx4 v[18:21], v[88:89], off offset:-2048 nt
	global_load_dwordx4 v[14:17], v[88:89], off offset:-1024 nt
	global_load_dwordx4 v[46:49], v[88:89], off nt
	global_load_dwordx4 v[42:45], v[88:89], off offset:1024 nt
	global_load_dwordx4 v[38:41], v[88:89], off offset:2048 nt
	global_load_dwordx4 v[34:37], v[88:89], off offset:3072 nt
